# v_c7 + write-through (sc1) output stores in the scan (ODN) and gate (MIX) halves, which finish ~25 us before their phase's barrier, so the barrier's L2 writeback has less to flush
# speedup vs baseline: 1.0008x; 1.0008x over previous
.LBB0_1354:
	ds_read_b128 v[152:155], v150
	ds_read_b128 v[156:159], v150 offset:64
	s_waitcnt vmcnt(4)
	v_lshlrev_b32_e32 v160, 16, v136
	v_and_b32_e32 v161, 0xffff0000, v136
	v_lshlrev_b32_e32 v136, 16, v137
	s_waitcnt lgkmcnt(1)
	v_mfma_f32_16x16x32_bf16 v[86:89], v[86:89], v[152:155], 0
	v_and_b32_e32 v137, 0xffff0000, v137
	s_add_i32 s41, s19, 1
	v_readlane_b32 s42, v149, s41
	s_waitcnt lgkmcnt(0)
	v_mfma_f32_16x16x32_bf16 v[86:89], v[90:93], v[156:159], v[86:89]
	ds_read_b128 v[90:93], v150 offset:128
	s_add_i32 s19, s19, 2
	v_lshl_add_u64 v[126:127], v[126:127], 0, s[30:31]
	v_mfma_f32_16x16x32_bf16 v[58:61], v[58:61], v[152:155], 0
	v_lshl_add_u64 v[128:129], v[128:129], 0, s[62:63]
	v_lshl_add_u64 v[130:131], v[130:131], 0, s[30:31]
	v_lshl_add_u64 v[132:133], v[132:133], 0, s[30:31]
	s_waitcnt lgkmcnt(0)
	v_mfma_f32_16x16x32_bf16 v[86:89], v[94:97], v[90:93], v[86:89]
	ds_read_b128 v[94:97], v150 offset:192
	v_mfma_f32_16x16x32_bf16 v[58:61], v[66:69], v[156:159], v[58:61]
	s_waitcnt lgkmcnt(0)
	v_mfma_f32_16x16x32_bf16 v[82:85], v[82:85], v[94:97], v[86:89]
	v_mfma_f32_16x16x32_bf16 v[58:61], v[62:65], v[90:93], v[58:61]
	v_mfma_f32_16x16x32_bf16 v[58:61], v[70:73], v[94:97], v[58:61]
	s_nop 5
	v_add_f32_e64 v82, v160, -v82
	v_add_f32_e64 v83, v161, -v83
	v_pk_add_f32 v[84:85], v[136:137], v[84:85] neg_lo:[0,1] neg_hi:[0,1]
	v_cvt_pk_bf16_f32 v82, v82, v83
	v_cvt_pk_bf16_f32 v83, v84, v85
	ds_write_b64 v146, v[82:83] offset:8704
	s_waitcnt lgkmcnt(0)
	s_barrier
	ds_read_b128 v[62:65], v151 offset:8704
	ds_read_b128 v[66:69], v151 offset:8768
	v_add_u32_e32 v70, 64, v124
	v_ashrrev_i32_e32 v71, 31, v70
	s_waitcnt lgkmcnt(1)
	v_mfma_f32_16x16x32_bf16 v[58:61], v[74:77], v[62:65], v[58:61]
	v_lshlrev_b64 v[62:63], 12, v[70:71]
	v_lshl_add_u64 v[74:75], v[122:123], 0, v[62:63]
	ds_read_b128 v[62:65], v147 offset:8704
	ds_read_b128 v[70:73], v147 offset:8768
	s_waitcnt lgkmcnt(2)
	v_mfma_f32_16x16x32_bf16 v[58:61], v[78:81], v[66:69], v[58:61]
	v_mul_f32_e64 v68, v104, s42
	v_mul_f32_e64 v69, v105, s42
	v_pk_mul_f32 v[66:67], v[102:103], s[42:43] op_sel_hi:[1,0]
	v_add_co_u32_e32 v76, vcc, s33, v74
	s_waitcnt lgkmcnt(1)
	v_mfma_f32_16x16x32_bf16 v[62:65], v[54:57], v[62:65], v[66:69]
	v_addc_co_u32_e32 v77, vcc, 0, v75, vcc
	s_nop 0
	global_store_dword v[74:75], v58, off sc1
	s_waitcnt lgkmcnt(0)
	v_mfma_f32_16x16x32_bf16 v[102:105], v[50:53], v[70:73], v[62:65]
	global_store_dword v[76:77], v59, off offset:-4096 sc1
	v_pk_mul_f32 v[68:69], v[100:101], s[42:43] op_sel_hi:[1,0]
	v_pk_mul_f32 v[66:67], v[98:99], s[42:43] op_sel_hi:[1,0]
	v_add_u32_e32 v124, 0x80, v124
	global_store_dword v[76:77], v60, off sc1
	s_nop 2
	v_cvt_pk_bf16_f32 v58, v102, v103
	v_cvt_pk_bf16_f32 v59, v104, v105
	ds_write_b64 v148, v[58:59]
	ds_read_b128 v[62:65], v147 offset:11008
	ds_read_b128 v[70:73], v147 offset:11072
	s_waitcnt lgkmcnt(1)
	v_mfma_f32_16x16x32_bf16 v[54:57], v[54:57], v[62:65], v[66:69]
	v_add_co_u32_e32 v58, vcc, s74, v74
	s_waitcnt lgkmcnt(0)
	v_mfma_f32_16x16x32_bf16 v[98:101], v[50:53], v[70:73], v[54:57]
	v_addc_co_u32_e32 v59, vcc, 0, v75, vcc
	s_and_b64 vcc, exec, s[16:17]
	global_store_dword v[58:59], v61, off sc1
	s_nop 4
	v_cvt_pk_bf16_f32 v50, v98, v99
	v_cvt_pk_bf16_f32 v51, v100, v101
	ds_write_b64 v148, v[50:51] offset:4352
	s_cbranch_vccnz .LBB0_1349
.LBB0_1355:
	v_lshl_add_u64 v[50:51], s[0:1], 0, v[126:127]
	s_mov_b32 s16, 0x34704000
	v_add_co_u32_e32 v52, vcc, s16, v50
	s_mov_b32 s16, 0x35704000
	s_nop 0
	v_addc_co_u32_e32 v53, vcc, 0, v51, vcc
	v_add_co_u32_e32 v50, vcc, s16, v50
	s_waitcnt lgkmcnt(0)
	s_nop 0
	v_addc_co_u32_e32 v51, vcc, 0, v51, vcc
	s_barrier
	global_load_dwordx4 v[86:89], v[52:53], off
	global_load_dwordx4 v[58:61], v[50:51], off
	global_load_dwordx4 v[90:93], v[52:53], off offset:1024
	global_load_dwordx4 v[66:69], v[50:51], off offset:1024
	global_load_dwordx4 v[94:97], v[52:53], off offset:2048
	global_load_dwordx4 v[62:65], v[50:51], off offset:2048
	global_load_dwordx4 v[82:85], v[52:53], off offset:3072
	global_load_dwordx4 v[70:73], v[50:51], off offset:3072
	v_lshl_add_u64 v[50:51], s[0:1], 0, v[128:129]
	s_mov_b32 s16, 0x37702000
	v_add_co_u32_e32 v50, vcc, s16, v50
	v_lshl_add_u64 v[52:53], s[0:1], 0, v[130:131]
	s_nop 0
	v_addc_co_u32_e32 v51, vcc, 0, v51, vcc
	s_mov_b32 s16, 0x36704000
	v_add_co_u32_e32 v52, vcc, s16, v52
	global_load_dwordx4 v[74:77], v[50:51], off
	s_nop 0
	v_addc_co_u32_e32 v53, vcc, 0, v53, vcc
	global_load_dwordx4 v[54:57], v[52:53], off
	global_load_dwordx4 v[78:81], v[50:51], off offset:1024
	s_nop 0
	global_load_dwordx4 v[50:53], v[52:53], off offset:1024
	v_lshl_add_u64 v[136:137], s[0:1], 0, v[132:133]
	global_load_dwordx2 v[136:137], v[136:137], off
	v_add_u32_e32 v150, v140, v141
	ds_read_b128 v[152:155], v150
	ds_read_b128 v[156:159], v150 offset:64
	ds_read_b128 v[160:163], v150 offset:128
	ds_read_b128 v[164:167], v150 offset:192
	s_waitcnt vmcnt(25) lgkmcnt(3)
	v_mfma_f32_16x16x32_bf16 v[168:171], v[2:5], v[152:155], 0
	s_waitcnt vmcnt(13)
	v_lshlrev_b32_e32 v172, 16, v134
	v_and_b32_e32 v173, 0xffff0000, v134
	v_add_u32_e32 v151, v142, v141
	s_waitcnt lgkmcnt(2)
	v_mfma_f32_16x16x32_bf16 v[168:171], v[6:9], v[156:159], v[168:171]
	v_ashrrev_i32_e32 v125, 31, v124
	v_readlane_b32 s16, v149, s19
	s_cmp_gt_u32 s19, 29
	s_waitcnt lgkmcnt(1)
	v_mfma_f32_16x16x32_bf16 v[168:171], v[14:17], v[160:163], v[168:171]
	v_mul_f32_e64 v104, v104, s16
	v_mul_f32_e64 v105, v105, s16
	v_pk_mul_f32 v[102:103], v[102:103], s[16:17] op_sel_hi:[1,0]
	v_pk_mul_f32 v[100:101], v[100:101], s[16:17] op_sel_hi:[1,0]
	v_mfma_f32_16x16x32_bf16 v[152:155], v[18:21], v[152:155], 0
	v_mul_f32_e64 v98, v98, s16
	v_mul_f32_e64 v99, v99, s16
	s_cselect_b64 s[16:17], -1, 0
	s_waitcnt lgkmcnt(0)
	v_mfma_f32_16x16x32_bf16 v[168:171], v[26:29], v[164:167], v[168:171]
	v_mfma_f32_16x16x32_bf16 v[152:155], v[10:13], v[156:159], v[152:155]
	v_mfma_f32_16x16x32_bf16 v[152:155], v[22:25], v[160:163], v[152:155]
	s_nop 5
	v_add_f32_e64 v168, v172, -v168
	v_add_f32_e64 v169, v173, -v169
	v_lshlrev_b32_e32 v172, 16, v135
	v_and_b32_e32 v173, 0xffff0000, v135
	v_pk_add_f32 v[170:171], v[172:173], v[170:171] neg_lo:[0,1] neg_hi:[0,1]
	v_cvt_pk_bf16_f32 v168, v168, v169
	v_cvt_pk_bf16_f32 v169, v170, v171
	ds_write_b64 v146, v[168:169] offset:8704
	s_waitcnt lgkmcnt(0)
	s_barrier
	ds_read_b128 v[156:159], v151 offset:8704
	v_mfma_f32_16x16x32_bf16 v[152:155], v[30:33], v[164:167], v[152:155]
	s_waitcnt lgkmcnt(0)
	v_mfma_f32_16x16x32_bf16 v[152:155], v[34:37], v[156:159], v[152:155]
	ds_read_b128 v[156:159], v151 offset:8768
	s_waitcnt lgkmcnt(0)
	v_mfma_f32_16x16x32_bf16 v[152:155], v[42:45], v[156:159], v[152:155]
	v_lshlrev_b64 v[156:157], 12, v[124:125]
	v_lshl_add_u64 v[156:157], v[122:123], 0, v[156:157]
	v_add_co_u32_e32 v158, vcc, s33, v156
	s_nop 4
	global_store_dword v[156:157], v152, off sc1
	v_addc_co_u32_e32 v159, vcc, 0, v157, vcc
	v_add_co_u32_e32 v152, vcc, s74, v156
	global_store_dword v[158:159], v153, off offset:-4096 sc1
	global_store_dword v[158:159], v154, off sc1
	v_addc_co_u32_e32 v153, vcc, 0, v157, vcc
	global_store_dword v[152:153], v155, off sc1
	ds_read_b128 v[152:155], v147 offset:8704
	s_waitcnt lgkmcnt(0)
	v_mfma_f32_16x16x32_bf16 v[102:105], v[38:41], v[152:155], v[102:105]
	ds_read_b128 v[152:155], v147 offset:8768
	s_and_b64 vcc, exec, s[16:17]
	s_waitcnt lgkmcnt(0)
	v_mfma_f32_16x16x32_bf16 v[102:105], v[46:49], v[152:155], v[102:105]
	s_nop 7
	v_cvt_pk_bf16_f32 v152, v102, v103
	v_cvt_pk_bf16_f32 v153, v104, v105
	ds_write_b64 v148, v[152:153]
	ds_read_b128 v[152:155], v147 offset:11008
	s_waitcnt lgkmcnt(0)
	v_mfma_f32_16x16x32_bf16 v[98:101], v[38:41], v[152:155], v[98:101]
	ds_read_b128 v[152:155], v147 offset:11072
	s_waitcnt lgkmcnt(0)
	v_mfma_f32_16x16x32_bf16 v[98:101], v[46:49], v[152:155], v[98:101]
	s_nop 7
	v_cvt_pk_bf16_f32 v152, v98, v99
	v_cvt_pk_bf16_f32 v153, v100, v101
	ds_write_b64 v148, v[152:153] offset:4352
	s_waitcnt lgkmcnt(0)
	s_barrier
	s_cbranch_vccnz .LBB0_1354
	s_add_i32 s42, s18, s19
	s_ashr_i32 s43, s42, 31
	s_lshl_b64 s[44:45], s[42:43], 13
	s_lshl_b64 s[42:43], s[42:43], 14
	v_lshl_add_u64 v[22:23], v[108:109], 0, s[42:43]
	v_lshl_add_u64 v[30:31], v[110:111], 0, s[42:43]
	global_load_dwordx4 v[2:5], v[22:23], off
	global_load_dwordx4 v[6:9], v[22:23], off offset:1024
	global_load_dwordx4 v[18:21], v[30:31], off
	global_load_dwordx4 v[10:13], v[30:31], off offset:1024
	global_load_dwordx4 v[14:17], v[22:23], off offset:2048
	global_load_dwordx4 v[26:29], v[22:23], off offset:3072
	s_nop 0
	global_load_dwordx4 v[22:25], v[30:31], off offset:2048
	s_nop 0
	global_load_dwordx4 v[30:33], v[30:31], off offset:3072
	v_lshl_add_u64 v[38:39], v[112:113], 0, s[44:45]
	v_lshl_add_u64 v[46:47], v[116:117], 0, s[42:43]
	global_load_dwordx4 v[34:37], v[38:39], off
	global_load_dwordx4 v[42:45], v[38:39], off offset:1024
	s_nop 0
	global_load_dwordx4 v[38:41], v[46:47], off
	s_nop 0
	global_load_dwordx4 v[46:49], v[46:47], off offset:1024
	v_lshl_add_u64 v[134:135], v[120:121], 0, s[42:43]
	global_load_dwordx2 v[134:135], v[134:135], off
	s_branch .LBB0_1354

; __device__ __forceinline__ unsigned pk2(float lo, float hi) { const f32x2 v = {lo, hi}; const bf16x2_n b = __builtin_convertvector(v, bf16x2_n); return __builtin_bit_cast(unsigned, b); }
; __device__ __forceinline__ float lo_bf(unsigned w) { return __uint_as_float(w << 16); }
; __device__ __forceinline__ float hi_bf(unsigned w) { return __uint_as_float(w & 0xffff0000u); }
; __device__ __forceinline__ float silu_f(float x) { return x * __builtin_amdgcn_rcpf(1.0f + __expf(-x)); }
; __device__ __forceinline__ void dn_gate_phase(const float* ODN, const bf16* PROJ, const float* norm_g, bf16* MIX, int G, int wave_s) {
;     ...
;     for (int m = gw; m < MTOK; m += NGW) {
;         f32x2 o[8]; unsigned zz[8];
; #pragma unroll
;         for (int h = 0; h < 8; ++h) { o[h] = *(const f32x2*)(ODN + (size_t)m * 1024 + h * 128 + 2 * lane); zz[h] = *(const unsigned*)(PROJ + (size_t)m * PLD + 3072 + h * 128 + 2 * lane); }
; #pragma unroll
;         for (int h = 0; h < 8; ++h) { const float ss = wave_sum(o[h].x * o[h].x + o[h].y * o[h].y), r = __builtin_amdgcn_rsqf(ss * (1.0f / 128.0f) + LN_EPS);
;             *(unsigned*)(MIX + (size_t)m * DM + h * 128 + 2 * lane) = pk2(o[h].x * r * g2.x * silu_f(lo_bf(zz[h])), o[h].y * r * g2.y * silu_f(hi_bf(zz[h]))); }
.LBB0_1646:
	v_lshl_add_u64 v[12:13], s[16:17], 0, v[10:11]
	v_add_co_u32_e32 v12, vcc, 0x31700000, v12
	v_lshl_add_u64 v[14:15], s[16:17], 0, v[6:7]
	s_nop 0
	v_addc_co_u32_e32 v13, vcc, 0, v13, vcc
	global_load_dwordx2 v[20:21], v[12:13], off
	v_add_co_u32_e32 v22, vcc, 0x1ee01000, v14
	s_mov_b32 s7, 0x24e00000
	s_nop 0
	v_addc_co_u32_e32 v23, vcc, 0, v15, vcc
	global_load_dword v3, v[22:23], off offset:2048
	global_load_dwordx2 v[24:25], v[12:13], off offset:512
	global_load_dword v34, v[22:23], off offset:2304
	global_load_dwordx2 v[26:27], v[12:13], off offset:1024
	global_load_dword v35, v[22:23], off offset:2560
	global_load_dwordx2 v[28:29], v[12:13], off offset:1536
	global_load_dword v36, v[22:23], off offset:2816
	global_load_dwordx2 v[18:19], v[12:13], off offset:2048
	global_load_dword v37, v[22:23], off offset:3072
	global_load_dwordx2 v[16:17], v[12:13], off offset:2560
	global_load_dword v38, v[22:23], off offset:3328
	global_load_dwordx2 v[14:15], v[12:13], off offset:3072
	global_load_dword v39, v[22:23], off offset:3584
	s_nop 0
	global_load_dwordx2 v[12:13], v[12:13], off offset:3584
	s_nop 0
	global_load_dword v40, v[22:23], off offset:3840
	v_lshl_add_u64 v[22:23], s[16:17], 0, v[8:9]
	v_add_u32_e32 v2, s6, v2
	v_lshl_add_u64 v[6:7], v[6:7], 0, s[8:9]
	v_lshl_add_u64 v[10:11], v[10:11], 0, s[10:11]
	v_lshl_add_u64 v[8:9], v[8:9], 0, s[10:11]
	s_waitcnt vmcnt(15)
	v_pk_mul_f32 v[30:31], v[20:21], v[20:21]
	s_nop 0
	v_add_f32_e32 v0, v30, v31
	s_waitcnt vmcnt(14)
	v_and_b32_e32 v31, 0xffff0000, v3
	v_add_f32_dpp v0, v0, v0 row_ror:8 row_mask:0xf bank_mask:0xf bound_ctrl:1
	s_nop 1
	v_add_f32_dpp v0, v0, v0 row_ror:4 row_mask:0xf bank_mask:0xf bound_ctrl:1
	s_nop 1
	v_add_f32_dpp v0, v0, v0 row_ror:2 row_mask:0xf bank_mask:0xf bound_ctrl:1
	s_nop 1
	v_add_f32_dpp v0, v0, v0 row_ror:1 row_mask:0xf bank_mask:0xf bound_ctrl:1
	v_mov_b32_e32 v30, v0
	s_nop 1
	v_permlane16_swap_b32_e32 v0, v30
	v_add_f32_e32 v0, v0, v30
	v_mov_b32_e32 v30, v0
	s_nop 1
	v_permlane32_swap_b32_e32 v0, v30
	v_add_f32_e32 v0, v0, v30
	v_fmamk_f32 v0, v0, 0x3c000000, v216
	v_rsq_f32_e32 v0, v0
	v_lshlrev_b32_e32 v30, 16, v3
	v_mul_f32_e32 v3, 0xbfb8aa3b, v30
	v_exp_f32_e32 v3, v3
	v_pk_mul_f32 v[20:21], v[20:21], v[0:1] op_sel_hi:[1,0]
	v_mul_f32_e32 v0, 0xbfb8aa3b, v31
	v_exp_f32_e32 v0, v0
	v_add_f32_e32 v3, 1.0, v3
	v_rcp_f32_e32 v32, v3
	v_pk_mul_f32 v[20:21], v[4:5], v[20:21]
	v_add_f32_e32 v0, 1.0, v0
	v_rcp_f32_e32 v33, v0
	s_nop 0
	v_pk_mul_f32 v[30:31], v[32:33], v[30:31]
	s_nop 0
	v_pk_mul_f32 v[20:21], v[30:31], v[20:21]
	s_nop 0
	v_cvt_pk_bf16_f32 v0, v20, v21
	v_add_co_u32_e32 v20, vcc, s7, v22
	s_movk_i32 s7, 0x1fff
	s_nop 0
	v_addc_co_u32_e32 v21, vcc, 0, v23, vcc
	s_waitcnt vmcnt(13)
	v_pk_mul_f32 v[22:23], v[24:25], v[24:25]
	global_store_dword v[20:21], v0, off sc1
	v_add_f32_e32 v0, v22, v23
	s_waitcnt vmcnt(13)
	v_lshlrev_b32_e32 v22, 16, v34
	v_and_b32_e32 v23, 0xffff0000, v34
	v_add_f32_dpp v0, v0, v0 row_ror:8 row_mask:0xf bank_mask:0xf bound_ctrl:1
	v_cmp_lt_i32_e32 vcc, s7, v2
	s_or_b64 s[12:13], vcc, s[12:13]
	v_add_f32_dpp v0, v0, v0 row_ror:4 row_mask:0xf bank_mask:0xf bound_ctrl:1
	s_nop 1
	v_add_f32_dpp v0, v0, v0 row_ror:2 row_mask:0xf bank_mask:0xf bound_ctrl:1
	s_nop 1
	v_add_f32_dpp v0, v0, v0 row_ror:1 row_mask:0xf bank_mask:0xf bound_ctrl:1
	v_mov_b32_e32 v3, v0
	s_nop 1
	v_permlane16_swap_b32_e32 v0, v3
	v_add_f32_e32 v0, v0, v3
	v_mov_b32_e32 v3, v0
	s_nop 1
	v_permlane32_swap_b32_e32 v0, v3
	v_add_f32_e32 v0, v0, v3
	v_fmamk_f32 v0, v0, 0x3c000000, v216
	v_rsq_f32_e32 v0, v0
	v_mul_f32_e32 v3, 0xbfb8aa3b, v22
	v_exp_f32_e32 v3, v3
	v_pk_mul_f32 v[24:25], v[24:25], v[0:1] op_sel_hi:[1,0]
	v_mul_f32_e32 v0, 0xbfb8aa3b, v23
	v_exp_f32_e32 v0, v0
	v_add_f32_e32 v3, 1.0, v3
	v_rcp_f32_e32 v30, v3
	v_pk_mul_f32 v[24:25], v[4:5], v[24:25]
	v_add_f32_e32 v0, 1.0, v0
	v_rcp_f32_e32 v31, v0
	s_nop 0
	v_pk_mul_f32 v[22:23], v[30:31], v[22:23]
	s_nop 0
	v_pk_mul_f32 v[22:23], v[22:23], v[24:25]
	s_nop 0
	v_cvt_pk_bf16_f32 v0, v22, v23
	s_waitcnt vmcnt(12)
	v_pk_mul_f32 v[22:23], v[26:27], v[26:27]
	global_store_dword v[20:21], v0, off offset:256 sc1
	v_add_f32_e32 v0, v22, v23
	s_waitcnt vmcnt(12)
	v_lshlrev_b32_e32 v22, 16, v35
	v_and_b32_e32 v23, 0xffff0000, v35
	v_add_f32_dpp v0, v0, v0 row_ror:8 row_mask:0xf bank_mask:0xf bound_ctrl:1
	s_nop 1
	v_add_f32_dpp v0, v0, v0 row_ror:4 row_mask:0xf bank_mask:0xf bound_ctrl:1
	s_nop 1
	v_add_f32_dpp v0, v0, v0 row_ror:2 row_mask:0xf bank_mask:0xf bound_ctrl:1
	s_nop 1
	v_add_f32_dpp v0, v0, v0 row_ror:1 row_mask:0xf bank_mask:0xf bound_ctrl:1
	v_mov_b32_e32 v3, v0
	s_nop 1
	v_permlane16_swap_b32_e32 v0, v3
	v_add_f32_e32 v0, v0, v3
	v_mov_b32_e32 v3, v0
	s_nop 1
	v_permlane32_swap_b32_e32 v0, v3
	v_add_f32_e32 v0, v0, v3
	v_fmamk_f32 v0, v0, 0x3c000000, v216
	v_rsq_f32_e32 v0, v0
	v_mul_f32_e32 v3, 0xbfb8aa3b, v22
	v_exp_f32_e32 v3, v3
	v_pk_mul_f32 v[26:27], v[26:27], v[0:1] op_sel_hi:[1,0]
	v_mul_f32_e32 v0, 0xbfb8aa3b, v23
	v_exp_f32_e32 v0, v0
	v_add_f32_e32 v3, 1.0, v3
	v_rcp_f32_e32 v24, v3
	v_pk_mul_f32 v[26:27], v[4:5], v[26:27]
	v_add_f32_e32 v0, 1.0, v0
	v_rcp_f32_e32 v25, v0
	s_nop 0
	v_pk_mul_f32 v[22:23], v[24:25], v[22:23]
	s_nop 0
	v_pk_mul_f32 v[22:23], v[22:23], v[26:27]
	s_nop 0
	v_cvt_pk_bf16_f32 v0, v22, v23
	s_waitcnt vmcnt(11)
	v_pk_mul_f32 v[22:23], v[28:29], v[28:29]
	global_store_dword v[20:21], v0, off offset:512 sc1
	v_add_f32_e32 v0, v22, v23
	s_waitcnt vmcnt(11)
; __device__ __forceinline__ unsigned pk2(float lo, float hi) { const f32x2 v = {lo, hi}; const bf16x2_n b = __builtin_convertvector(v, bf16x2_n); return __builtin_bit_cast(unsigned, b); }
; __device__ __forceinline__ float lo_bf(unsigned w) { return __uint_as_float(w << 16); }
; __device__ __forceinline__ float hi_bf(unsigned w) { return __uint_as_float(w & 0xffff0000u); }
; __device__ __forceinline__ float silu_f(float x) { return x * __builtin_amdgcn_rcpf(1.0f + __expf(-x)); }
; __device__ __forceinline__ void dn_gate_phase(const float* ODN, const bf16* PROJ, const float* norm_g, bf16* MIX, int G, int wave_s) {
;     ...
;         for (int h = 0; h < 8; ++h) { const float ss = wave_sum(o[h].x * o[h].x + o[h].y * o[h].y), r = __builtin_amdgcn_rsqf(ss * (1.0f / 128.0f) + LN_EPS);
;             *(unsigned*)(MIX + (size_t)m * DM + h * 128 + 2 * lane) = pk2(o[h].x * r * g2.x * silu_f(lo_bf(zz[h])), o[h].y * r * g2.y * silu_f(hi_bf(zz[h]))); }
	v_lshlrev_b32_e32 v22, 16, v36
	v_and_b32_e32 v23, 0xffff0000, v36
	v_add_f32_dpp v0, v0, v0 row_ror:8 row_mask:0xf bank_mask:0xf bound_ctrl:1
	s_nop 1
	v_add_f32_dpp v0, v0, v0 row_ror:4 row_mask:0xf bank_mask:0xf bound_ctrl:1
	s_nop 1
	v_add_f32_dpp v0, v0, v0 row_ror:2 row_mask:0xf bank_mask:0xf bound_ctrl:1
	s_nop 1
	v_add_f32_dpp v0, v0, v0 row_ror:1 row_mask:0xf bank_mask:0xf bound_ctrl:1
	v_mov_b32_e32 v3, v0
	s_nop 1
	v_permlane16_swap_b32_e32 v0, v3
	v_add_f32_e32 v0, v0, v3
	v_mov_b32_e32 v3, v0
	s_nop 1
	v_permlane32_swap_b32_e32 v0, v3
	v_add_f32_e32 v0, v0, v3
	v_fmamk_f32 v0, v0, 0x3c000000, v216
	v_rsq_f32_e32 v0, v0
	v_mul_f32_e32 v3, 0xbfb8aa3b, v22
	v_exp_f32_e32 v3, v3
	v_pk_mul_f32 v[26:27], v[28:29], v[0:1] op_sel_hi:[1,0]
	v_mul_f32_e32 v0, 0xbfb8aa3b, v23
	v_exp_f32_e32 v0, v0
	v_add_f32_e32 v3, 1.0, v3
	v_rcp_f32_e32 v24, v3
	v_pk_mul_f32 v[26:27], v[4:5], v[26:27]
	v_add_f32_e32 v0, 1.0, v0
	v_rcp_f32_e32 v25, v0
	s_nop 0
	v_pk_mul_f32 v[22:23], v[24:25], v[22:23]
	s_nop 0
	v_pk_mul_f32 v[22:23], v[22:23], v[26:27]
	s_nop 0
	v_cvt_pk_bf16_f32 v0, v22, v23
	s_waitcnt vmcnt(10)
	v_pk_mul_f32 v[22:23], v[18:19], v[18:19]
	global_store_dword v[20:21], v0, off offset:768 sc1
	v_add_f32_e32 v0, v22, v23
	s_waitcnt vmcnt(10)
	v_lshlrev_b32_e32 v22, 16, v37
	v_and_b32_e32 v23, 0xffff0000, v37
	v_add_f32_dpp v0, v0, v0 row_ror:8 row_mask:0xf bank_mask:0xf bound_ctrl:1
	s_nop 1
	v_add_f32_dpp v0, v0, v0 row_ror:4 row_mask:0xf bank_mask:0xf bound_ctrl:1
	s_nop 1
	v_add_f32_dpp v0, v0, v0 row_ror:2 row_mask:0xf bank_mask:0xf bound_ctrl:1
	s_nop 1
	v_add_f32_dpp v0, v0, v0 row_ror:1 row_mask:0xf bank_mask:0xf bound_ctrl:1
	v_mov_b32_e32 v3, v0
	s_nop 1
	v_permlane16_swap_b32_e32 v0, v3
	v_add_f32_e32 v0, v0, v3
	v_mov_b32_e32 v3, v0
	s_nop 1
	v_permlane32_swap_b32_e32 v0, v3
	v_add_f32_e32 v0, v0, v3
	v_fmamk_f32 v0, v0, 0x3c000000, v216
	v_rsq_f32_e32 v0, v0
	v_mul_f32_e32 v3, 0xbfb8aa3b, v22
	v_exp_f32_e32 v3, v3
	v_pk_mul_f32 v[18:19], v[18:19], v[0:1] op_sel_hi:[1,0]
	v_mul_f32_e32 v0, 0xbfb8aa3b, v23
	v_exp_f32_e32 v0, v0
	v_add_f32_e32 v3, 1.0, v3
	v_rcp_f32_e32 v24, v3
	v_pk_mul_f32 v[18:19], v[4:5], v[18:19]
	v_add_f32_e32 v0, 1.0, v0
	v_rcp_f32_e32 v25, v0
	s_nop 0
	v_pk_mul_f32 v[22:23], v[24:25], v[22:23]
	s_nop 0
	v_pk_mul_f32 v[18:19], v[22:23], v[18:19]
	s_nop 0
	v_cvt_pk_bf16_f32 v0, v18, v19
	s_waitcnt vmcnt(9)
	v_pk_mul_f32 v[18:19], v[16:17], v[16:17]
	global_store_dword v[20:21], v0, off offset:1024 sc1
	v_add_f32_e32 v0, v18, v19
	s_waitcnt vmcnt(9)
	v_lshlrev_b32_e32 v18, 16, v38
	v_and_b32_e32 v19, 0xffff0000, v38
	v_add_f32_dpp v0, v0, v0 row_ror:8 row_mask:0xf bank_mask:0xf bound_ctrl:1
	s_nop 1
	v_add_f32_dpp v0, v0, v0 row_ror:4 row_mask:0xf bank_mask:0xf bound_ctrl:1
	s_nop 1
	v_add_f32_dpp v0, v0, v0 row_ror:2 row_mask:0xf bank_mask:0xf bound_ctrl:1
	s_nop 1
	v_add_f32_dpp v0, v0, v0 row_ror:1 row_mask:0xf bank_mask:0xf bound_ctrl:1
	v_mov_b32_e32 v3, v0
	s_nop 1
	v_permlane16_swap_b32_e32 v0, v3
	v_add_f32_e32 v0, v0, v3
	v_mov_b32_e32 v3, v0
	s_nop 1
	v_permlane32_swap_b32_e32 v0, v3
	v_add_f32_e32 v0, v0, v3
	v_fmamk_f32 v0, v0, 0x3c000000, v216
	v_rsq_f32_e32 v0, v0
	v_mul_f32_e32 v3, 0xbfb8aa3b, v18
	v_exp_f32_e32 v3, v3
	v_pk_mul_f32 v[16:17], v[16:17], v[0:1] op_sel_hi:[1,0]
	v_mul_f32_e32 v0, 0xbfb8aa3b, v19
	v_exp_f32_e32 v0, v0
	v_add_f32_e32 v3, 1.0, v3
	v_rcp_f32_e32 v22, v3
	v_pk_mul_f32 v[16:17], v[4:5], v[16:17]
	v_add_f32_e32 v0, 1.0, v0
	v_rcp_f32_e32 v23, v0
	s_nop 0
	v_pk_mul_f32 v[18:19], v[22:23], v[18:19]
	s_nop 0
	v_pk_mul_f32 v[16:17], v[18:19], v[16:17]
	s_nop 0
	v_cvt_pk_bf16_f32 v0, v16, v17
	s_waitcnt vmcnt(8)
	v_pk_mul_f32 v[16:17], v[14:15], v[14:15]
	global_store_dword v[20:21], v0, off offset:1280 sc1
	v_add_f32_e32 v0, v16, v17
	s_waitcnt vmcnt(8)
	v_lshlrev_b32_e32 v16, 16, v39
	v_and_b32_e32 v17, 0xffff0000, v39
	v_add_f32_dpp v0, v0, v0 row_ror:8 row_mask:0xf bank_mask:0xf bound_ctrl:1
	s_nop 1
	v_add_f32_dpp v0, v0, v0 row_ror:4 row_mask:0xf bank_mask:0xf bound_ctrl:1
	s_nop 1
	v_add_f32_dpp v0, v0, v0 row_ror:2 row_mask:0xf bank_mask:0xf bound_ctrl:1
	s_nop 1
	v_add_f32_dpp v0, v0, v0 row_ror:1 row_mask:0xf bank_mask:0xf bound_ctrl:1
	v_mov_b32_e32 v3, v0
	s_nop 1
	v_permlane16_swap_b32_e32 v0, v3
	v_add_f32_e32 v0, v0, v3
	v_mov_b32_e32 v3, v0
	s_nop 1
	v_permlane32_swap_b32_e32 v0, v3
	v_add_f32_e32 v0, v0, v3
	v_fmamk_f32 v0, v0, 0x3c000000, v216
	v_rsq_f32_e32 v0, v0
	v_mul_f32_e32 v3, 0xbfb8aa3b, v16
	v_exp_f32_e32 v3, v3
	v_pk_mul_f32 v[14:15], v[14:15], v[0:1] op_sel_hi:[1,0]
	v_mul_f32_e32 v0, 0xbfb8aa3b, v17
	v_exp_f32_e32 v0, v0
	v_add_f32_e32 v3, 1.0, v3
	v_rcp_f32_e32 v18, v3
	v_pk_mul_f32 v[14:15], v[4:5], v[14:15]
	v_add_f32_e32 v0, 1.0, v0
	v_rcp_f32_e32 v19, v0
	s_nop 0
	v_pk_mul_f32 v[16:17], v[18:19], v[16:17]
	s_nop 0
	v_pk_mul_f32 v[14:15], v[16:17], v[14:15]
	s_nop 0
	v_cvt_pk_bf16_f32 v0, v14, v15
	s_waitcnt vmcnt(7)
	v_pk_mul_f32 v[14:15], v[12:13], v[12:13]
	global_store_dword v[20:21], v0, off offset:1536 sc1
	v_add_f32_e32 v0, v14, v15
	s_waitcnt vmcnt(7)
	v_lshlrev_b32_e32 v14, 16, v40
	v_and_b32_e32 v15, 0xffff0000, v40
	v_add_f32_dpp v0, v0, v0 row_ror:8 row_mask:0xf bank_mask:0xf bound_ctrl:1
	s_nop 1
	v_add_f32_dpp v0, v0, v0 row_ror:4 row_mask:0xf bank_mask:0xf bound_ctrl:1
	s_nop 1
	v_add_f32_dpp v0, v0, v0 row_ror:2 row_mask:0xf bank_mask:0xf bound_ctrl:1
	s_nop 1
	v_add_f32_dpp v0, v0, v0 row_ror:1 row_mask:0xf bank_mask:0xf bound_ctrl:1
	v_mov_b32_e32 v3, v0
	s_nop 1
	v_permlane16_swap_b32_e32 v0, v3
	v_add_f32_e32 v0, v0, v3
	v_mov_b32_e32 v3, v0
	s_nop 1
	v_permlane32_swap_b32_e32 v0, v3
	v_add_f32_e32 v0, v0, v3
	v_fmamk_f32 v0, v0, 0x3c000000, v216
	v_rsq_f32_e32 v0, v0
	v_mul_f32_e32 v3, 0xbfb8aa3b, v14
	v_exp_f32_e32 v3, v3
	v_pk_mul_f32 v[12:13], v[12:13], v[0:1] op_sel_hi:[1,0]
	v_mul_f32_e32 v0, 0xbfb8aa3b, v15
	v_exp_f32_e32 v0, v0
	v_add_f32_e32 v3, 1.0, v3
	v_rcp_f32_e32 v16, v3
	v_pk_mul_f32 v[12:13], v[4:5], v[12:13]
	v_add_f32_e32 v0, 1.0, v0
	v_rcp_f32_e32 v17, v0
	s_nop 0
	v_pk_mul_f32 v[14:15], v[16:17], v[14:15]
	s_nop 0
	v_pk_mul_f32 v[12:13], v[14:15], v[12:13]
	s_nop 0
	v_cvt_pk_bf16_f32 v0, v12, v13
	global_store_dword v[20:21], v0, off offset:1792 sc1
	s_andn2_b64 exec, exec, s[12:13]
	s_cbranch_execnz .LBB0_1646
